# prep k/v transpose LDS tile: chunk-rotation swizzle removes 16-way bank conflicts on the transposed 2-byte reads
# speedup vs baseline: 1.0073x; 1.0073x over previous
.LBB0_621:
	s_or_b64 exec, exec, s[80:81]
	v_lshlrev_b64 v[2:3], 2, v[44:45]
	v_lshl_add_u64 v[4:5], s[66:67], 0, v[2:3]
	global_load_dwordx4 v[60:63], v[4:5], off offset:16
	global_load_dwordx4 v[64:67], v[4:5], off
	s_nop 0
	flat_load_dwordx4 v[4:7], v[0:1]
	v_lshl_add_u64 v[68:69], s[68:69], 0, v[2:3]
	global_load_dwordx4 v[0:3], v[68:69], off offset:16
	s_nop 0
	global_load_dwordx4 v[68:71], v[68:69], off
	s_waitcnt vmcnt(0) lgkmcnt(0)
	v_lshlrev_b32_e32 v72, 16, v16
	v_and_b32_e32 v16, 0xffff0000, v16
	v_fma_f32 v33, v33, v16, 0
	v_lshlrev_b32_e32 v16, 16, v17
	v_fma_f32 v34, v34, v16, 0
	v_and_b32_e32 v16, 0xffff0000, v17
	v_fma_f32 v72, v32, v72, 0
	v_fma_f32 v32, v35, v16, 0
	v_lshlrev_b32_e32 v16, 16, v18
	v_fma_f32 v24, v24, v16, 0
	v_and_b32_e32 v16, 0xffff0000, v18
	v_fma_f32 v18, v25, v16, 0
	v_lshlrev_b32_e32 v16, 16, v19
	v_fma_f32 v17, v26, v16, 0
	v_and_b32_e32 v16, 0xffff0000, v19
	v_lshlrev_b32_e32 v19, 16, v8
	v_and_b32_e32 v8, 0xffff0000, v8
	v_fmac_f32_e32 v33, v29, v8
	v_lshlrev_b32_e32 v8, 16, v9
	v_fmac_f32_e32 v34, v30, v8
	v_and_b32_e32 v8, 0xffff0000, v9
	v_fmac_f32_e32 v32, v31, v8
	v_lshlrev_b32_e32 v8, 16, v10
	v_fmac_f32_e32 v24, v20, v8
	v_and_b32_e32 v8, 0xffff0000, v10
	v_fmac_f32_e32 v18, v21, v8
	v_lshlrev_b32_e32 v8, 16, v11
	v_fma_f32 v16, v27, v16, 0
	v_fmac_f32_e32 v17, v22, v8
	v_and_b32_e32 v8, 0xffff0000, v11
	v_fmac_f32_e32 v72, v28, v19
	v_fmac_f32_e32 v16, v23, v8
	v_lshlrev_b32_e32 v8, 16, v12
	s_waitcnt vmcnt(0)
	v_fmac_f32_e32 v72, v64, v8
	v_and_b32_e32 v8, 0xffff0000, v12
	v_fmac_f32_e32 v33, v65, v8
	v_lshlrev_b32_e32 v8, 16, v13
	v_fmac_f32_e32 v34, v66, v8
	v_and_b32_e32 v8, 0xffff0000, v13
	v_fmac_f32_e32 v32, v67, v8
	v_lshlrev_b32_e32 v8, 16, v14
	v_fmac_f32_e32 v24, v60, v8
	v_and_b32_e32 v8, 0xffff0000, v14
	v_fmac_f32_e32 v18, v61, v8
	v_lshlrev_b32_e32 v8, 16, v15
	v_fmac_f32_e32 v17, v62, v8
	v_and_b32_e32 v8, 0xffff0000, v15
	v_fmac_f32_e32 v16, v63, v8
	v_lshlrev_b32_e32 v8, 16, v4
	v_and_b32_e32 v4, 0xffff0000, v4
	v_fmac_f32_e32 v33, v69, v4
	v_lshlrev_b32_e32 v4, 16, v5
	v_fmac_f32_e32 v34, v70, v4
	v_and_b32_e32 v4, 0xffff0000, v5
	v_fmac_f32_e32 v32, v71, v4
	v_lshlrev_b32_e32 v4, 16, v6
	v_fmac_f32_e32 v24, v0, v4
	v_and_b32_e32 v0, 0xffff0000, v6
	v_fmac_f32_e32 v18, v1, v0
	v_lshlrev_b32_e32 v0, 16, v7
	v_fmac_f32_e32 v72, v68, v8
	v_fmac_f32_e32 v17, v2, v0
	v_and_b32_e32 v0, 0xffff0000, v7
	v_fmac_f32_e32 v16, v3, v0
	v_mul_f32_e32 v0, 0xbfb8aa3b, v72
	v_exp_f32_e32 v0, v0
	s_nop 0
	v_add_f32_e32 v0, 1.0, v0
	v_div_scale_f32 v1, s[20:21], v0, v0, v72
	v_rcp_f32_e32 v2, v1
	s_nop 0
	v_fma_f32 v3, -v1, v2, 1.0
	v_fmac_f32_e32 v2, v3, v2
	v_div_scale_f32 v3, vcc, v72, v0, v72
	v_mul_f32_e32 v4, v3, v2
	v_fma_f32 v5, -v1, v4, v3
	v_fmac_f32_e32 v4, v5, v2
	v_fma_f32 v1, -v1, v4, v3
	v_div_fmas_f32 v1, v1, v2, v4
	v_div_fixup_f32 v0, v1, v0, v72
	v_mul_f32_e32 v1, 0xbfb8aa3b, v33
	v_exp_f32_e32 v1, v1
	v_mul_f32_e32 v0, 0x3d93cd3a, v0
	v_add_f32_e32 v1, 1.0, v1
	v_div_scale_f32 v2, s[20:21], v1, v1, v33
	v_rcp_f32_e32 v3, v2
	s_nop 0
	v_fma_f32 v4, -v2, v3, 1.0
	v_fmac_f32_e32 v3, v4, v3
	v_div_scale_f32 v4, vcc, v33, v1, v33
	v_mul_f32_e32 v5, v4, v3
	v_fma_f32 v6, -v2, v5, v4
	v_fmac_f32_e32 v5, v6, v3
	v_fma_f32 v2, -v2, v5, v4
	v_div_fmas_f32 v2, v2, v3, v5
	v_div_fixup_f32 v1, v2, v1, v33
	v_mul_f32_e32 v2, 0xbfb8aa3b, v34
	v_exp_f32_e32 v2, v2
	v_mul_f32_e32 v1, 0x3d93cd3a, v1
	v_cvt_pk_bf16_f32 v0, v0, v1
	v_add_f32_e32 v2, 1.0, v2
	v_div_scale_f32 v3, s[20:21], v2, v2, v34
	v_rcp_f32_e32 v4, v3
	s_nop 0
	v_fma_f32 v5, -v3, v4, 1.0
	v_fmac_f32_e32 v4, v5, v4
	v_div_scale_f32 v5, vcc, v34, v2, v34
	v_mul_f32_e32 v6, v5, v4
	v_fma_f32 v7, -v3, v6, v5
	v_fmac_f32_e32 v6, v7, v4
	v_fma_f32 v3, -v3, v6, v5
	v_div_fmas_f32 v3, v3, v4, v6
	v_div_fixup_f32 v2, v3, v2, v34
	v_mul_f32_e32 v3, 0xbfb8aa3b, v32
	v_exp_f32_e32 v3, v3
	v_mul_f32_e32 v2, 0x3d93cd3a, v2
	v_add_f32_e32 v3, 1.0, v3
	v_div_scale_f32 v4, s[20:21], v3, v3, v32
	v_rcp_f32_e32 v5, v4
	s_nop 0
	v_fma_f32 v6, -v4, v5, 1.0
	v_fmac_f32_e32 v5, v6, v5
	v_div_scale_f32 v6, vcc, v32, v3, v32
	v_mul_f32_e32 v7, v6, v5
	v_fma_f32 v8, -v4, v7, v6
	v_fmac_f32_e32 v7, v8, v5
	v_fma_f32 v4, -v4, v7, v6
	v_div_fmas_f32 v4, v4, v5, v7
	v_div_fixup_f32 v3, v4, v3, v32
	v_mul_f32_e32 v4, 0xbfb8aa3b, v24
	v_exp_f32_e32 v4, v4
	v_mul_f32_e32 v3, 0x3d93cd3a, v3
	v_cvt_pk_bf16_f32 v1, v2, v3
	v_add_f32_e32 v4, 1.0, v4
	v_div_scale_f32 v5, s[20:21], v4, v4, v24
	v_rcp_f32_e32 v6, v5
	s_nop 0
	v_fma_f32 v7, -v5, v6, 1.0
	v_fmac_f32_e32 v6, v7, v6
	v_div_scale_f32 v7, vcc, v24, v4, v24
	v_mul_f32_e32 v8, v7, v6
	v_fma_f32 v9, -v5, v8, v7
	v_fmac_f32_e32 v8, v9, v6
	v_fma_f32 v5, -v5, v8, v7
	v_div_fmas_f32 v5, v5, v6, v8
	v_div_fixup_f32 v4, v5, v4, v24
	v_mul_f32_e32 v5, 0xbfb8aa3b, v18
	v_exp_f32_e32 v5, v5
	v_mul_f32_e32 v4, 0x3d93cd3a, v4
	v_add_f32_e32 v5, 1.0, v5
	v_div_scale_f32 v6, s[20:21], v5, v5, v18
	v_rcp_f32_e32 v7, v6
	s_nop 0
	v_fma_f32 v8, -v6, v7, 1.0
	v_fmac_f32_e32 v7, v8, v7
	v_div_scale_f32 v8, vcc, v18, v5, v18
	v_mul_f32_e32 v9, v8, v7
	v_fma_f32 v10, -v6, v9, v8
	v_fmac_f32_e32 v9, v10, v7
	v_fma_f32 v6, -v6, v9, v8
	v_div_fmas_f32 v6, v6, v7, v9
	v_div_fixup_f32 v5, v6, v5, v18
	v_mul_f32_e32 v6, 0xbfb8aa3b, v17
	v_exp_f32_e32 v6, v6
	v_mul_f32_e32 v5, 0x3d93cd3a, v5
	v_cvt_pk_bf16_f32 v2, v4, v5
	v_lshl_add_u64 v[4:5], v[46:47], 1, s[60:61]
	v_add_f32_e32 v6, 1.0, v6
	v_div_scale_f32 v7, s[20:21], v6, v6, v17
	v_rcp_f32_e32 v8, v7
	v_lshl_add_u64 v[4:5], v[44:45], 1, v[4:5]
	v_fma_f32 v9, -v7, v8, 1.0
	v_fmac_f32_e32 v8, v9, v8
	v_div_scale_f32 v9, vcc, v17, v6, v17
	v_mul_f32_e32 v10, v9, v8
	v_fma_f32 v11, -v7, v10, v9
	v_fmac_f32_e32 v10, v11, v8
	v_fma_f32 v7, -v7, v10, v9
	v_div_fmas_f32 v7, v7, v8, v10
	v_div_fixup_f32 v6, v7, v6, v17
	v_mul_f32_e32 v7, 0xbfb8aa3b, v16
	v_exp_f32_e32 v7, v7
	v_mul_f32_e32 v6, 0x3d93cd3a, v6
	v_add_f32_e32 v7, 1.0, v7
	v_div_scale_f32 v8, s[20:21], v7, v7, v16
	v_rcp_f32_e32 v9, v8
	s_nop 0
	v_fma_f32 v10, -v8, v9, 1.0
	v_fmac_f32_e32 v9, v10, v9
	v_div_scale_f32 v10, vcc, v16, v7, v16
	v_mul_f32_e32 v11, v10, v9
	v_fma_f32 v12, -v8, v11, v10
	v_fmac_f32_e32 v11, v12, v9
	v_fma_f32 v8, -v8, v11, v10
	v_div_fmas_f32 v8, v8, v9, v11
	v_div_fixup_f32 v7, v8, v7, v16
	v_mul_f32_e32 v7, 0x3d93cd3a, v7
	v_cvt_pk_bf16_f32 v3, v6, v7
	flat_store_dwordx4 v[4:5], v[0:3]
	v_lshrrev_b32_e32 v140, 3, v44
	v_lshrrev_b32_e32 v138, 3, v36
	v_add_u32_e32 v140, v140, v138
	v_subrev_u32_e32 v138, 25, v140
	v_cmp_gt_u32_e64 s[20:21], 25, v140
	s_nop 1
	v_cndmask_b32_e64 v140, v138, v140, s[20:21]
	v_lshlrev_b32_e32 v4, 4, v140
	v_mad_u32_u24 v4, v36, s94, v4
	ds_write_b128 v4, v[0:3]
	v_add_u32_e32 v0, 0x200, v43
	v_cmp_lt_u32_e32 vcc, s95, v43
	s_or_b64 s[70:71], vcc, s[70:71]
	v_mov_b32_e32 v43, v0
	s_andn2_b64 exec, exec, s[70:71]
	s_cbranch_execz .LBB0_628

.LBB0_629:
	v_and_b32_e32 v5, 0x78, v3
	v_lshrrev_b32_e32 v140, 4, v2
	v_bfe_u32 v141, v3, 3, 4
	v_add_u32_e32 v140, v140, v141
	v_subrev_u32_e32 v141, 25, v140
	v_cmp_gt_u32_e64 s[20:21], 25, v140
	s_nop 1
	v_cndmask_b32_e64 v140, v141, v140, s[20:21]
	v_and_b32_e32 v141, 15, v2
	v_lshl_or_b32 v140, v140, 4, v141
	v_mad_u32_u24 v5, v5, s94, v140
	ds_read_u16 v6, v5
	ds_read_u16 v7, v5 offset:400
	v_add_u32_e32 v4, 0x200, v4
	v_cmp_lt_u32_e32 vcc, s95, v4
	v_add_u32_e32 v3, 0x1000, v3
	v_add_u32_e32 v2, 64, v2
	s_waitcnt lgkmcnt(0)
	v_lshl_or_b32 v6, v7, 16, v6
	ds_read_u16 v7, v5 offset:800
	ds_read_u16 v8, v5 offset:1200
	s_or_b64 s[60:61], vcc, s[60:61]
	s_waitcnt lgkmcnt(0)
	v_lshl_or_b32 v7, v8, 16, v7
	ds_read_u16 v8, v5 offset:1600
	ds_read_u16 v9, v5 offset:2000
	s_waitcnt lgkmcnt(0)
	v_lshl_or_b32 v8, v9, 16, v8
	ds_read_u16 v9, v5 offset:2400
	ds_read_u16 v5, v5 offset:2800
	s_waitcnt lgkmcnt(0)
	v_lshl_or_b32 v9, v5, 16, v9
	flat_store_dwordx4 v[0:1], v[6:9]
	v_lshl_add_u64 v[0:1], v[0:1], 0, s[36:37]
	s_andn2_b64 exec, exec, s[60:61]
	s_cbranch_execnz .LBB0_629
	s_or_b64 exec, exec, s[60:61]
	s_lshl_b32 s20, s34, 1
	s_add_u32 s60, s83, s20
	s_addc_u32 s61, s84, 0
	s_mov_b64 s[62:63], 0
	v_mov_b32_e32 v0, v176
	s_waitcnt lgkmcnt(0)
	s_barrier
.LBB0_631:
	v_mov_b32_e32 v137, 0
	v_mul_u32_u24_e32 v96, 0xaaab, v176
	v_lshrrev_b32_e32 v136, 20, v96
	v_mov_b64_e32 v[130:131], s[60:61]
	s_movk_i32 s20, 0xffe8
	v_lshl_add_u64 v[132:133], s[56:57], 0, v[136:137]
	v_mad_i32_i24 v96, v136, s20, v176
	v_mad_u64_u32 v[130:131], s[20:21], v132, s96, v[130:131]
	v_mov_b32_e32 v132, v131
	v_lshlrev_b32_e32 v134, 3, v96
	v_mad_u64_u32 v[132:133], s[20:21], v133, s96, v[132:133]
	v_ashrrev_i32_e32 v135, 31, v134
	v_mov_b32_e32 v131, v132
	v_lshl_add_u64 v[130:131], v[134:135], 1, v[130:131]
	global_load_dwordx4 v[100:103], v[130:131], off
	v_lshrrev_b32_e32 v138, 3, v136
	v_add_u32_e32 v96, v96, v138
	v_subrev_u32_e32 v138, 25, v96
	v_cmp_gt_u32_e64 s[20:21], 25, v96
	s_nop 1
	v_cndmask_b32_e64 v96, v138, v96, s[20:21]
	v_lshlrev_b32_e32 v96, 4, v96
	v_mad_u32_u24 v124, v136, s94, v96
	v_add_u32_e32 v99, 0x200, v176
	v_mul_u32_u24_e32 v96, 0xaaab, v99
	v_lshrrev_b32_e32 v136, 20, v96
	v_mov_b64_e32 v[130:131], s[60:61]
	s_movk_i32 s20, 0xffe8
	v_lshl_add_u64 v[132:133], s[56:57], 0, v[136:137]
	v_mad_i32_i24 v96, v136, s20, v99
	v_mad_u64_u32 v[130:131], s[20:21], v132, s96, v[130:131]
	v_mov_b32_e32 v132, v131
	v_lshlrev_b32_e32 v134, 3, v96
	v_mad_u64_u32 v[132:133], s[20:21], v133, s96, v[132:133]
	v_ashrrev_i32_e32 v135, 31, v134
	v_mov_b32_e32 v131, v132
	v_lshl_add_u64 v[130:131], v[134:135], 1, v[130:131]
	global_load_dwordx4 v[104:107], v[130:131], off
	v_lshrrev_b32_e32 v138, 3, v136
	v_add_u32_e32 v96, v96, v138
	v_subrev_u32_e32 v138, 25, v96
	v_cmp_gt_u32_e64 s[20:21], 25, v96
	s_nop 1
	v_cndmask_b32_e64 v96, v138, v96, s[20:21]
	v_lshlrev_b32_e32 v96, 4, v96
	v_mad_u32_u24 v125, v136, s94, v96
	v_add_u32_e32 v99, 0x400, v176
	v_mul_u32_u24_e32 v96, 0xaaab, v99
	v_lshrrev_b32_e32 v136, 20, v96
	v_mov_b64_e32 v[130:131], s[60:61]
	s_movk_i32 s20, 0xffe8
	v_lshl_add_u64 v[132:133], s[56:57], 0, v[136:137]
	v_mad_i32_i24 v96, v136, s20, v99
	v_mad_u64_u32 v[130:131], s[20:21], v132, s96, v[130:131]
	v_mov_b32_e32 v132, v131
	v_lshlrev_b32_e32 v134, 3, v96
	v_mad_u64_u32 v[132:133], s[20:21], v133, s96, v[132:133]
	v_ashrrev_i32_e32 v135, 31, v134
	v_mov_b32_e32 v131, v132
	v_lshl_add_u64 v[130:131], v[134:135], 1, v[130:131]
	global_load_dwordx4 v[108:111], v[130:131], off
	v_lshrrev_b32_e32 v138, 3, v136
	v_add_u32_e32 v96, v96, v138
	v_subrev_u32_e32 v138, 25, v96
	v_cmp_gt_u32_e64 s[20:21], 25, v96
	s_nop 1
	v_cndmask_b32_e64 v96, v138, v96, s[20:21]
	v_lshlrev_b32_e32 v96, 4, v96
	v_mad_u32_u24 v126, v136, s94, v96
	v_add_u32_e32 v99, 0x600, v176
	v_mul_u32_u24_e32 v96, 0xaaab, v99
	v_lshrrev_b32_e32 v136, 20, v96
	v_mov_b64_e32 v[130:131], s[60:61]
	s_movk_i32 s20, 0xffe8
	v_lshl_add_u64 v[132:133], s[56:57], 0, v[136:137]
	v_mad_i32_i24 v96, v136, s20, v99
	v_mad_u64_u32 v[130:131], s[20:21], v132, s96, v[130:131]
	v_mov_b32_e32 v132, v131
	v_lshlrev_b32_e32 v134, 3, v96
	v_mad_u64_u32 v[132:133], s[20:21], v133, s96, v[132:133]
	v_ashrrev_i32_e32 v135, 31, v134
	v_mov_b32_e32 v131, v132
	v_lshl_add_u64 v[130:131], v[134:135], 1, v[130:131]
	global_load_dwordx4 v[112:115], v[130:131], off
	v_lshrrev_b32_e32 v138, 3, v136
	v_add_u32_e32 v96, v96, v138
	v_subrev_u32_e32 v138, 25, v96
	v_cmp_gt_u32_e64 s[20:21], 25, v96
	s_nop 1
	v_cndmask_b32_e64 v96, v138, v96, s[20:21]
	v_lshlrev_b32_e32 v96, 4, v96
	v_mad_u32_u24 v127, v136, s94, v96
	v_add_u32_e32 v99, 0x800, v176
	v_mul_u32_u24_e32 v96, 0xaaab, v99
	v_lshrrev_b32_e32 v136, 20, v96
	v_mov_b64_e32 v[130:131], s[60:61]
	s_movk_i32 s20, 0xffe8
	v_lshl_add_u64 v[132:133], s[56:57], 0, v[136:137]
	v_mad_i32_i24 v96, v136, s20, v99
	v_mad_u64_u32 v[130:131], s[20:21], v132, s96, v[130:131]
	v_mov_b32_e32 v132, v131
	v_lshlrev_b32_e32 v134, 3, v96
	v_mad_u64_u32 v[132:133], s[20:21], v133, s96, v[132:133]
	v_ashrrev_i32_e32 v135, 31, v134
	v_mov_b32_e32 v131, v132
	v_lshl_add_u64 v[130:131], v[134:135], 1, v[130:131]
	global_load_dwordx4 v[116:119], v[130:131], off
	v_lshrrev_b32_e32 v138, 3, v136
	v_add_u32_e32 v96, v96, v138
	v_subrev_u32_e32 v138, 25, v96
	v_cmp_gt_u32_e64 s[20:21], 25, v96
	s_nop 1
	v_cndmask_b32_e64 v96, v138, v96, s[20:21]
	v_lshlrev_b32_e32 v96, 4, v96
	v_mad_u32_u24 v128, v136, s94, v96
	v_add_u32_e32 v99, 0xa00, v176
	v_mul_u32_u24_e32 v96, 0xaaab, v99
	v_lshrrev_b32_e32 v136, 20, v96
	v_mov_b64_e32 v[130:131], s[60:61]
	s_movk_i32 s20, 0xffe8
	v_lshl_add_u64 v[132:133], s[56:57], 0, v[136:137]
	v_mad_i32_i24 v96, v136, s20, v99
	v_mad_u64_u32 v[130:131], s[20:21], v132, s96, v[130:131]
	v_mov_b32_e32 v132, v131
	v_lshlrev_b32_e32 v134, 3, v96
	v_mad_u64_u32 v[132:133], s[20:21], v133, s96, v[132:133]
	v_ashrrev_i32_e32 v135, 31, v134
	v_mov_b32_e32 v131, v132
	v_lshl_add_u64 v[130:131], v[134:135], 1, v[130:131]
	global_load_dwordx4 v[120:123], v[130:131], off
	v_lshrrev_b32_e32 v138, 3, v136
	v_add_u32_e32 v96, v96, v138
	v_subrev_u32_e32 v138, 25, v96
	v_cmp_gt_u32_e64 s[20:21], 25, v96
	s_nop 1
	v_cndmask_b32_e64 v96, v138, v96, s[20:21]
	v_lshlrev_b32_e32 v96, 4, v96
	v_mad_u32_u24 v129, v136, s94, v96
	v_mov_b32_e32 v36, v136
	s_waitcnt vmcnt(0)
	ds_write_b128 v124, v[100:103]
	ds_write_b128 v125, v[104:107]
	ds_write_b128 v126, v[108:111]
	ds_write_b128 v127, v[112:115]
	ds_write_b128 v128, v[116:119]
	ds_write_b128 v129, v[120:123]
	s_or_b64 exec, exec, s[62:63]
	v_lshl_add_u64 v[0:1], v[40:41], 0, s[58:59]
	s_mov_b64 s[56:57], 0
	v_mov_b32_e32 v2, v53
	v_mov_b32_e32 v3, v52
	v_mov_b32_e32 v4, v51
	s_waitcnt lgkmcnt(0)
	s_barrier
.LBB0_633:
	v_and_b32_e32 v5, 0x78, v3
	v_lshrrev_b32_e32 v140, 4, v2
	v_bfe_u32 v141, v3, 3, 4
	v_add_u32_e32 v140, v140, v141
	v_subrev_u32_e32 v141, 25, v140
	v_cmp_gt_u32_e64 s[20:21], 25, v140
	s_nop 1
	v_cndmask_b32_e64 v140, v141, v140, s[20:21]
	v_and_b32_e32 v141, 15, v2
	v_lshl_or_b32 v140, v140, 4, v141
	v_mad_u32_u24 v5, v5, s94, v140
	ds_read_u16 v6, v5
	ds_read_u16 v7, v5 offset:400
	v_add_u32_e32 v4, 0x200, v4
	v_cmp_lt_u32_e32 vcc, s95, v4
	v_add_u32_e32 v3, 0x1000, v3
	v_add_u32_e32 v2, 64, v2
	s_waitcnt lgkmcnt(0)
	v_lshl_or_b32 v6, v7, 16, v6
	ds_read_u16 v7, v5 offset:800
	ds_read_u16 v8, v5 offset:1200
	s_or_b64 s[56:57], vcc, s[56:57]
	s_waitcnt lgkmcnt(0)
	v_lshl_or_b32 v7, v8, 16, v7
	ds_read_u16 v8, v5 offset:1600
	ds_read_u16 v9, v5 offset:2000
	s_waitcnt lgkmcnt(0)
	v_lshl_or_b32 v8, v9, 16, v8
	ds_read_u16 v9, v5 offset:2400
	ds_read_u16 v5, v5 offset:2800
	s_waitcnt lgkmcnt(0)
	v_lshl_or_b32 v9, v5, 16, v9
	flat_store_dwordx4 v[0:1], v[6:9]
	v_lshl_add_u64 v[0:1], v[0:1], 0, s[36:37]
	s_andn2_b64 exec, exec, s[56:57]
	s_cbranch_execnz .LBB0_633
	s_or_b64 exec, exec, s[56:57]
	s_load_dword s34, s[18:19], 0x0
	s_waitcnt lgkmcnt(0)
	s_add_i32 s38, s34, s38
	s_cmpk_gt_i32 s38, 0x3ff
	s_cbranch_scc0 .LBB0_599
	v_readlane_b32 s4, v253, 0
	v_readlane_b32 s5, v253, 1
	s_load_dwordx4 s[92:95], s[4:5], 0xe0
	v_readlane_b32 s90, v253, 56
	v_readlane_b32 s97, v253, 58
	v_readlane_b32 s91, v253, 57
